# wait half of the attention->RNN grid barrier deferred to the RNN loop's first copy-out (the first stores into regions attention reads); all roles poll the top generation word
# baseline (speedup 1.0000x reference)
; __device__ __forceinline__ int lane_id() { int l; asm volatile("v_mbcnt_lo_u32_b32 %0, -1, 0\n\tv_mbcnt_hi_u32_b32 %0, -1, %0" : "=v"(l)); return l; }
; __device__ __forceinline__ unsigned xb_ld(unsigned* p)              { return __hip_atomic_load(p, __ATOMIC_RELAXED, __HIP_MEMORY_SCOPE_AGENT); }
; __device__ __forceinline__ unsigned xb_add(unsigned* p, unsigned v) { return __hip_atomic_fetch_add(p, v, __ATOMIC_RELAXED, __HIP_MEMORY_SCOPE_AGENT); }
; #define XB_SPIN(cond, bar) do { unsigned _sp = 0; while (cond) { __builtin_amdgcn_s_sleep(1); \
;     if ((++_sp & 255u) == 0u) { if (xb_ld(&(bar)[XB_TMO])) break; if (_sp > XB_SPIN_CAP) { atomicAdd(&(bar)[XB_TMO], 1u); break; } } } } while (0)
; __device__ __forceinline__ void xcd_wait(const XcdBarrier& b, const XcdTok& t) {
;     if (b.wave == 0 && lane_id() == 0) {
;         unsigned* bar = b.bar;
;         if (t.role >= 1) {
;             if (t.role == 1) XB_SPIN(xb_ld(&bar[XB_TOPGEN]) == t.tg, bar);
;             __builtin_amdgcn_fence(__ATOMIC_ACQUIRE, "agent");
;             xb_add(&bar[XB_XGEN(b.x)], 1u);
;             asm volatile("s_waitcnt vmcnt(0)" ::: "memory");
;         } else {
;             XB_SPIN(xb_ld(&bar[XB_XGEN(b.x)]) == t.gen, bar);
;             __builtin_amdgcn_fence(__ATOMIC_ACQUIRE, "agent");
;             asm volatile("s_waitcnt vmcnt(0)" ::: "memory");
;         }
;     }
;     __syncthreads();
; __device__ __forceinline__ void rnn_local_phase(Frame& F, const XcdBarrier& gbar, const bool use_bar) {
;     ...
;     if (use_bar) xcd_wait(gbar, tok);
.LBB0_577:
	s_mov_b32 s98, 0
	s_and_b64 vcc, exec, s[14:15]
	s_cbranch_vccz .Lrw_flags_done
	s_mov_b32 s98, 1
	v_readlane_b32 s12, v254, 9
	v_readlane_b32 s13, v254, 10
	s_nop 1
	s_and_b64 vcc, exec, s[12:13]
	s_cbranch_vccz .Lrw_flags_done
	s_or_b32 s98, s98, 8
	s_bitcmp1_b32 s18, 0
	s_cselect_b32 s12, 2, 0
	s_or_b32 s98, s98, s12
	v_readfirstlane_b32 s99, v75
.Lrw_flags_done:
	s_branch .LBB0_613
	v_readlane_b32 s12, v254, 9
	v_readlane_b32 s13, v254, 10
	s_andn2_b64 vcc, exec, s[12:13]
	s_cbranch_vccnz .LBB0_612
	v_mbcnt_lo_u32_b32 v67, -1, 0
	v_mbcnt_hi_u32_b32 v67, -1, v67
	s_nop 0
	v_cmp_eq_u32_e32 vcc, 0, v67
	s_and_saveexec_b64 s[14:15], vcc
	s_cbranch_execz .LBB0_611
	s_xor_b64 s[12:13], s[18:19], -1
	s_and_saveexec_b64 s[18:19], s[12:13]
	s_xor_b64 s[18:19], exec, s[18:19]
	s_cbranch_execz .LBB0_594
	v_readlane_b32 s1, v254, 8
	s_lshl_b32 s1, s1, 8
	v_readlane_b32 s12, v254, 6
	v_readlane_b32 s13, v254, 7
	s_add_u32 s12, s12, s1
	s_addc_u32 s13, s13, 0
	v_mov_b32_e32 v67, 0x2000
	s_add_u32 s24, s12, 0x2400
	s_addc_u32 s25, s13, 0
	global_load_dword v67, v67, s[12:13] offset:1024 sc1
	s_waitcnt vmcnt(0)
	v_cmp_eq_u32_e32 vcc, v67, v75
	s_and_saveexec_b64 s[20:21], vcc
	s_cbranch_execz .LBB0_593
	s_add_u32 s22, s10, 0x4200
	s_addc_u32 s23, s11, 0
	s_mov_b32 s1, 1
	s_mov_b64 s[26:27], 0
	v_mov_b32_e32 v67, 0
	s_branch .LBB0_584

; __device__ __forceinline__ int lane_id() { int l; asm volatile("v_mbcnt_lo_u32_b32 %0, -1, 0\n\tv_mbcnt_hi_u32_b32 %0, -1, %0" : "=v"(l)); return l; }
; #define GAS __attribute__((address_space(1)))
; #define LAS __attribute__((address_space(3)))
; __device__ __forceinline__ unsigned xb_ld(unsigned* p)              { return __hip_atomic_load(p, __ATOMIC_RELAXED, __HIP_MEMORY_SCOPE_AGENT); }
; __device__ __forceinline__ unsigned xb_add(unsigned* p, unsigned v) { return __hip_atomic_fetch_add(p, v, __ATOMIC_RELAXED, __HIP_MEMORY_SCOPE_AGENT); }
; #define XB_SPIN(cond, bar) do { unsigned _sp = 0; while (cond) { __builtin_amdgcn_s_sleep(1); \
;     if ((++_sp & 255u) == 0u) { if (xb_ld(&(bar)[XB_TMO])) break; if (_sp > XB_SPIN_CAP) { atomicAdd(&(bar)[XB_TMO], 1u); break; } } } } while (0)
; __device__ __forceinline__ void xcd_wait(const XcdBarrier& b, const XcdTok& t) {
;     if (b.wave == 0 && lane_id() == 0) {
;         unsigned* bar = b.bar;
;         if (t.role >= 1) {
;             if (t.role == 1) XB_SPIN(xb_ld(&bar[XB_TOPGEN]) == t.tg, bar);
;             __builtin_amdgcn_fence(__ATOMIC_ACQUIRE, "agent");
;             xb_add(&bar[XB_XGEN(b.x)], 1u);
;             asm volatile("s_waitcnt vmcnt(0)" ::: "memory");
; __device__ __forceinline__ void rnn_local_phase(Frame& F, const XcdBarrier& gbar, const bool use_bar) {
;     ...
;         asm volatile("s_waitcnt lgkmcnt(0)" ::: "memory"); __builtin_amdgcn_s_barrier(); asm volatile("" ::: "memory");
; #pragma unroll
;         for (int k = 0; k < 2; ++k) { const int idx = tid + 512 * k, tok = idx >> 4, ch = idx & 15;
;             const v4u v = *(const LAS v4u*)(lds + R_ST_OFF + tok * 256 + ch * 16);
;             *(GAS v4u*)(HL + (size_t)(t0 + tok) * DRNN + cb * 128 + ch * 8) = v; }
; #pragma unroll
;         for (int arr = 1; arr < 3; ++arr) {
;             unsigned char* dst = arr == 1 ? (unsigned char*)PF : (unsigned char*)PB; const int tok = tid >> 3, ch = tid & 7;
;             const v4u v = *(const LAS v4u*)(lds + R_ST_OFF + arr * 16384 + tok * 128 + ch * 16);
;             *(GAS v4u*)(dst + (size_t)(t0 + tok) * DRNN + cb * 128 + ch * 16) = v; }
.LBB0_615:
	s_or_b64 exec, exec, s[20:21]
	s_waitcnt lgkmcnt(0)
	s_bitcmp1_b32 s98, 0
	s_cbranch_scc0 .Lrw1_done
	s_andn2_b32 s98, s98, 1
	s_bitcmp1_b32 s98, 3
	s_cbranch_scc0 .Lrw1_done
	s_mov_b64 s[100:101], exec
	v_mbcnt_lo_u32_b32 v250, -1, 0
	v_mbcnt_hi_u32_b32 v250, -1, v250
	v_cmp_eq_u32_e32 vcc, 0, v250
	s_and_b64 exec, exec, vcc
	v_mov_b32_e32 v251, 0x7000
	v_mov_b32_e32 v253, 0
.Lrw1_spin:
	global_load_dword v252, v251, s[10:11] offset:1280 sc1
	s_waitcnt vmcnt(0)
	v_cmp_ne_u32_e32 vcc, s99, v252
	s_cbranch_vccnz .Lrw1_rel
	s_sleep 1
	v_add_u32_e32 v253, 1, v253
	v_cmp_gt_u32_e32 vcc, 0x40000, v253
	s_cbranch_vccnz .Lrw1_spin
.Lrw1_rel:
	s_bitcmp1_b32 s98, 1
	s_cbranch_scc0 .Lrw1_nolead
	v_readlane_b32 vcc_lo, v254, 6
	v_readlane_b32 vcc_hi, v254, 7
	v_readlane_b32 s99, v254, 8
	s_nop 1
	s_lshl_b32 s99, s99, 8
	s_add_u32 vcc_lo, vcc_lo, s99
	s_addc_u32 vcc_hi, vcc_hi, 0
	v_mov_b32_e32 v251, 0x2000
	v_mov_b32_e32 v252, 1
	s_nop 1
	global_atomic_add v251, v252, vcc offset:1024
	s_waitcnt vmcnt(0)
.Lrw1_nolead:
	s_mov_b64 exec, s[100:101]
.Lrw1_done:
	s_barrier
	ds_read_b128 v[84:87], v226 offset:16384
	v_add_u32_e32 v88, s17, v209
	v_mad_i64_i32 v[92:93], s[20:21], v88, s24, v[176:177]
	ds_read_b128 v[88:91], v227 offset:16384
	s_waitcnt lgkmcnt(0)
	global_store_dwordx4 v[92:93], v[84:87], off
	s_mov_b32 s8, s33
	s_nop 0
	v_add_u32_e32 v84, s17, v208
	v_mad_i64_i32 v[84:85], s[20:21], v84, s24, v[176:177]
	global_store_dwordx4 v[84:85], v[88:91], off
	v_add_u32_e32 v84, s17, v207
	v_mad_i64_i32 v[92:93], s[20:21], v84, s27, v[178:179]
	ds_read_b128 v[84:87], v228 offset:32768
	ds_read_b128 v[88:91], v228 offset:49152
	v_add_co_u32_e32 v94, vcc, 0x13000000, v92
	s_add_i32 s17, s17, s23
	s_nop 0
	v_addc_co_u32_e32 v95, vcc, 0, v93, vcc
	s_waitcnt lgkmcnt(0)
	global_store_dwordx4 v[94:95], v[84:87], off
	s_nop 1
	v_add_co_u32_e32 v84, vcc, 0x18000000, v92
	s_nop 1
	v_addc_co_u32_e32 v85, vcc, 0, v93, vcc
	s_andn2_b64 vcc, exec, s[18:19]
	global_store_dwordx4 v[84:85], v[88:91], off
	s_cbranch_vccz .LBB0_625

; __device__ __forceinline__ int lane_id() { int l; asm volatile("v_mbcnt_lo_u32_b32 %0, -1, 0\n\tv_mbcnt_hi_u32_b32 %0, -1, %0" : "=v"(l)); return l; }
; __device__ __forceinline__ unsigned xb_ld(unsigned* p)              { return __hip_atomic_load(p, __ATOMIC_RELAXED, __HIP_MEMORY_SCOPE_AGENT); }
; __device__ __forceinline__ unsigned xb_add(unsigned* p, unsigned v) { return __hip_atomic_fetch_add(p, v, __ATOMIC_RELAXED, __HIP_MEMORY_SCOPE_AGENT); }
; #define XB_SPIN(cond, bar) do { unsigned _sp = 0; while (cond) { __builtin_amdgcn_s_sleep(1); \
;     if ((++_sp & 255u) == 0u) { if (xb_ld(&(bar)[XB_TMO])) break; if (_sp > XB_SPIN_CAP) { atomicAdd(&(bar)[XB_TMO], 1u); break; } } } } while (0)
; __device__ __forceinline__ void xcd_wait(const XcdBarrier& b, const XcdTok& t) {
;     if (b.wave == 0 && lane_id() == 0) {
;         unsigned* bar = b.bar;
;         if (t.role >= 1) {
;             if (t.role == 1) XB_SPIN(xb_ld(&bar[XB_TOPGEN]) == t.tg, bar);
;             __builtin_amdgcn_fence(__ATOMIC_ACQUIRE, "agent");
;             xb_add(&bar[XB_XGEN(b.x)], 1u);
;             asm volatile("s_waitcnt vmcnt(0)" ::: "memory");
.LBB0_625:
	s_bitcmp1_b32 s98, 0
	s_cbranch_scc0 .Lrw2_done
	s_andn2_b32 s98, s98, 1
	s_bitcmp1_b32 s98, 3
	s_cbranch_scc0 .Lrw2_done
	s_mov_b64 s[100:101], exec
	v_mbcnt_lo_u32_b32 v250, -1, 0
	v_mbcnt_hi_u32_b32 v250, -1, v250
	v_cmp_eq_u32_e32 vcc, 0, v250
	s_and_b64 exec, exec, vcc
	v_mov_b32_e32 v251, 0x7000
	v_mov_b32_e32 v253, 0
